# v067 + GEMM prologues: the redundant first wait+barrier pair removed (both halves are symmetric there since v060; the second wait retires all of K-tile 0 before the remaining barrier)
# speedup vs baseline: 1.0033x; 1.0014x over previous
; #define PG8_STAGE(bufoff, gbase, voff) do { _Pragma("unroll") for (int _i = 0; _i < 2; ++_i) \
;         __builtin_amdgcn_global_load_lds((const unsigned*)((const char*)(gbase) + (voff)[_i]), (PG8_LAS unsigned*)(lds + (bufoff) + ldsw + _i * 8192), 16, 0, AUX_A); } while (0)
; #define PG8_STAGEB(bufoff, gbase, voff) do { _Pragma("unroll") for (int _i = 0; _i < 2; ++_i) \
;         __builtin_amdgcn_global_load_lds((const unsigned*)((const char*)(gbase) + (voff)[_i]), (PG8_LAS unsigned*)(lds + (bufoff) + ldsw + _i * 8192), 16, 0, AUX_B); } while (0)
; #define PG8_WAIT_V(n) asm volatile("s_waitcnt vmcnt(" #n ")" ::: "memory")
; #define PG8_BAR __builtin_amdgcn_s_barrier()
; template <class Epi, class Sched, bool ALIGN_EPI = false, bool SP2 = false>
; __device__ __forceinline__ void gemm_phase(PG8_LAS unsigned char* lds, const Gemm g, const Sched& S, const Epi& E) {
;     ...
;     const int aoff = lds_byte(wr * 64 + fr, fq * 8), boff = lds_byte(wc * 32 + fr, fq * 8);
;     ...
;         PG8_STAGEB(PG8_SB(1, 0), sB1, voffB); PG8_STAGE(PG8_SA(1, 0), sA1, voffA); PG8_STAGEB(PG8_SB(1, 1), sB1 + hstep, voffB);
;         PG8_WAIT_V(6); PG8_BAR;
.LBB0_264:
	v_readlane_b32 s2, v254, 53
	v_readlane_b32 s3, v254, 54
	v_readlane_b32 s44, v249, 50
	s_lshl_b64 s[6:7], s[2:3], 14
	v_readlane_b32 s50, v249, 56
	v_readlane_b32 s51, v249, 57
	s_add_u32 s4, s50, s6
	s_addc_u32 s5, s51, s7
	s_lshl_b32 s78, s2, 6
	s_lshl_b32 s31, s2, 4
	s_lshl_b32 s75, s2, 2
	s_add_u32 s20, s82, 0x1ec00000
	s_addc_u32 s21, s83, 0
	v_writelane_b32 v254, s4, 60
	s_add_u32 s22, s82, 0x26100000
	s_addc_u32 s23, s83, 0
	v_writelane_b32 v254, s5, 61
	s_mov_b64 s[4:5], s[82:83]
	s_add_u32 s82, s4, 0x27300000
	s_addc_u32 s83, s5, 0
	v_bfe_u32 v99, v16, 4, 2
	s_add_u32 s2, s4, 0x800000
	v_and_b32_e32 v1, 15, v16
	v_lshlrev_b32_e32 v17, 4, v99
	v_lshlrev_b32_e32 v16, 2, v16
	v_writelane_b32 v254, s4, 62
	s_addc_u32 s3, s5, 0
	s_and_b32 s18, s1, 3
	s_lshl_b32 s6, s0, 6
	v_lshl_or_b32 v17, v1, 6, v17
	s_lshl_b32 s0, s0, 13
	v_and_b32_e32 v16, 32, v16
	v_bitop3_b32 v18, v17, s0, v16 bitop3:0xde
	s_lshl_b32 s0, s18, 5
	s_add_i32 m0, s96, 0x18000
	v_lshl_add_u64 v[6:7], v[6:7], 0, s[76:77]
	v_writelane_b32 v255, s0, 0
	s_lshl_b32 s0, s18, 12
	global_load_lds_dwordx4 v[6:7], off
	v_lshl_add_u64 v[4:5], v[4:5], 0, s[76:77]
	s_add_i32 m0, s96, 0x1a000
	s_add_i32 s90, s96, 0x8000
	s_add_i32 s91, s96, 0xa000
	v_bitop3_b32 v221, v17, s0, v16 bitop3:0xde
	global_load_lds_dwordx4 v[4:5], off
	v_lshl_add_u64 v[2:3], v[2:3], 0, s[76:77]
	s_mov_b32 m0, s90
	s_add_u32 s0, s38, 0x80080
	global_load_lds_dwordx4 v[2:3], off
	v_lshl_add_u64 v[2:3], v[8:9], 0, s[76:77]
	s_mov_b32 m0, s91
	s_addc_u32 s1, s39, 0
	global_load_lds_dwordx4 v[2:3], off
	s_add_i32 m0, s96, 0x1c000
	v_lshl_add_u64 v[2:3], s[0:1], 0, v[184:185]
	global_load_lds_dwordx4 v[2:3], off
	v_lshl_add_u64 v[2:3], s[0:1], 0, v[180:181]
	s_add_i32 m0, s96, 0x1e000
	s_cmpk_lt_u32 s16, 0x100
	global_load_lds_dwordx4 v[2:3], off
	v_lshlrev_b32_e32 v2, 15, v10
	v_and_b32_e32 v2, 0xffff0000, v2
	v_lshl_add_u32 v2, v11, 12, v2
	v_and_b32_e32 v3, 1, v10
	v_lshl_or_b32 v2, v3, 6, v2
	s_cselect_b64 s[10:11], -1, 0
	s_lshl_b32 s0, s18, 6
	v_lshl_add_u32 v188, v12, 1, v2
	v_lshlrev_b32_e32 v2, 15, v14
	v_writelane_b32 v255, s0, 1
	s_or_b32 s93, s0, 0xfffffc00
	v_and_b32_e32 v2, 0xffff0000, v2
	s_lshl_b64 s[0:1], s[78:79], 2
	s_waitcnt vmcnt(6)
	v_lshl_add_u32 v2, v13, 12, v2
	v_and_b32_e32 v3, 1, v14
	v_writelane_b32 v255, s0, 2
	v_lshl_or_b32 v2, v3, 6, v2
	v_writelane_b32 v254, s5, 63
	v_writelane_b32 v255, s1, 3
	v_readlane_b32 s0, v252, 49
	v_mov_b32_e32 v189, v98
	v_lshl_add_u32 v190, v15, 1, v2
	v_mov_b32_e32 v191, v98
	s_mov_b32 s94, 0
	v_add_u32_e32 v222, 0, v18
	v_readlane_b32 s95, v253, 5
	s_mov_b32 s78, s0
	v_readlane_b32 s45, v249, 51
	v_readlane_b32 s46, v249, 52
	v_readlane_b32 s47, v249, 53
	v_readlane_b32 s48, v249, 54
	v_readlane_b32 s49, v249, 55
	v_readlane_b32 s52, v249, 58
	v_readlane_b32 s53, v249, 59
	v_readlane_b32 s54, v249, 60
	v_readlane_b32 s55, v249, 61
	v_readlane_b32 s56, v249, 62
	v_readlane_b32 s57, v249, 63
	v_readlane_b32 s58, v250, 0
	v_readlane_b32 s59, v250, 1
	s_barrier
	v_readlane_b32 s1, v252, 50
	s_branch .LBB0_267

; #define PG8_STAGE(bufoff, gbase, voff) do { _Pragma("unroll") for (int _i = 0; _i < 2; ++_i) \
;         __builtin_amdgcn_global_load_lds((const unsigned*)((const char*)(gbase) + (voff)[_i]), (PG8_LAS unsigned*)(lds + (bufoff) + ldsw + _i * 8192), 16, 0, AUX_A); } while (0)
; #define PG8_STAGEB(bufoff, gbase, voff) do { _Pragma("unroll") for (int _i = 0; _i < 2; ++_i) \
;         __builtin_amdgcn_global_load_lds((const unsigned*)((const char*)(gbase) + (voff)[_i]), (PG8_LAS unsigned*)(lds + (bufoff) + ldsw + _i * 8192), 16, 0, AUX_B); } while (0)
; #define PG8_WAIT_V(n) asm volatile("s_waitcnt vmcnt(" #n ")" ::: "memory")
; #define PG8_BAR __builtin_amdgcn_s_barrier()
; template <class Epi, class Sched, bool ALIGN_EPI = false, bool SP2 = false>
; __device__ __forceinline__ void gemm_phase(PG8_LAS unsigned char* lds, const Gemm g, const Sched& S, const Epi& E) {
;     ...
;     const int aoff = lds_byte(wr * 64 + fr, fq * 8), boff = lds_byte(wc * 32 + fr, fq * 8);
;     ...
;         PG8_STAGEB(PG8_SB(1, 0), sB1, voffB); PG8_STAGE(PG8_SA(1, 0), sA1, voffA); PG8_STAGEB(PG8_SB(1, 1), sB1 + hstep, voffB);
;         PG8_WAIT_V(6); PG8_BAR;
.LBB0_921:
	v_readlane_b32 s44, v249, 34
	s_lshl_b64 s[8:9], s[2:3], 12
	v_readlane_b32 s56, v249, 46
	v_readlane_b32 s57, v249, 47
	s_add_u32 s8, s56, s8
	v_lshrrev_b32_e32 v18, 1, v13
	s_addc_u32 s9, s57, s9
	v_and_b32_e32 v18, 24, v18
	s_add_u32 s10, s34, 0x28980000
	v_and_b32_e32 v17, 15, v13
	v_lshlrev_b32_e32 v19, 1, v18
	v_lshlrev_b32_e32 v13, 2, v13
	s_addc_u32 s11, s35, 0
	v_lshl_or_b32 v1, s0, 6, v17
	v_lshl_or_b32 v17, v17, 6, v19
	s_lshl_b32 s0, s0, 13
	v_and_b32_e32 v13, 32, v13
	v_bitop3_b32 v19, v17, s0, v13 bitop3:0xde
	s_lshl_b32 s0, s1, 5
	s_and_b32 s2, s0, 0x60
	s_add_i32 m0, s25, 0x18000
	v_lshl_add_u64 v[8:9], v[8:9], 0, s[76:77]
	s_lshl_b32 s0, s2, 7
	global_load_lds_dwordx4 v[8:9], off
	v_lshl_add_u64 v[6:7], v[6:7], 0, s[76:77]
	s_add_i32 m0, s25, 0x1a000
	s_add_i32 s70, s25, 0x8000
	s_add_i32 s71, s25, 0xa000
	v_bitop3_b32 v99, v17, s0, v13 bitop3:0xde
	global_load_lds_dwordx4 v[6:7], off
	v_lshl_add_u64 v[2:3], v[2:3], 0, s[76:77]
	s_mov_b32 m0, s70
	s_add_u32 s0, s26, 0x40080
	global_load_lds_dwordx4 v[2:3], off
	v_lshl_add_u64 v[2:3], v[4:5], 0, s[76:77]
	s_mov_b32 m0, s71
	s_addc_u32 s1, s27, 0
	global_load_lds_dwordx4 v[2:3], off
	s_add_i32 m0, s25, 0x1c000
	v_lshl_add_u64 v[2:3], s[0:1], 0, v[150:151]
	global_load_lds_dwordx4 v[2:3], off
	v_lshl_add_u64 v[2:3], s[0:1], 0, v[154:155]
	s_add_i32 m0, s25, 0x1e000
	v_readlane_b32 s45, v249, 35
	global_load_lds_dwordx4 v[2:3], off
	v_lshlrev_b32_e32 v2, 14, v14
	v_and_b32_e32 v2, 0xffff8000, v2
	v_lshl_add_u32 v2, v15, 11, v2
	v_and_b32_e32 v3, 1, v14
	v_lshl_or_b32 v2, v3, 6, v2
	v_lshl_add_u32 v156, v16, 1, v2
	v_lshlrev_b32_e32 v2, 14, v10
	v_and_b32_e32 v2, 0xffff8000, v2
	s_waitcnt vmcnt(6)
	v_lshl_add_u32 v2, v11, 11, v2
	v_and_b32_e32 v3, 1, v10
	v_readlane_b32 s48, v249, 38
	v_readlane_b32 s49, v249, 39
	v_readlane_b32 s50, v249, 40
	v_readlane_b32 s51, v249, 41
	s_cmpk_lt_u32 s12, 0x100
	v_lshl_or_b32 v2, v3, 6, v2
	s_cselect_b64 s[12:13], -1, 0
	v_or_b32_e32 v164, s2, v18
	v_mov_b32_e32 v157, v98
	v_lshl_add_u32 v158, v12, 1, v2
	v_mov_b32_e32 v159, v98
	s_mov_b32 s75, 0
	v_add_u32_e32 v165, 0, v19
	v_readlane_b32 s3, v252, 31
	v_readlane_b32 s44, v252, 33
	v_readlane_b32 s45, v252, 11
	v_readlane_b32 s48, v252, 12
	s_mov_b32 s49, 0x40000
	s_mov_b32 s50, 0x48000
	s_mov_b32 s51, 0x50000
	s_mov_b32 s66, 0x58000
	v_readlane_b32 s46, v249, 36
	v_readlane_b32 s47, v249, 37
	v_readlane_b32 s52, v249, 42
	v_readlane_b32 s53, v249, 43
	v_readlane_b32 s54, v249, 44
	v_readlane_b32 s55, v249, 45
	v_readlane_b32 s58, v249, 48
	v_readlane_b32 s59, v249, 49
	s_barrier
	s_branch .LBB0_924

; #define PG8_STAGE(bufoff, gbase, voff) do { _Pragma("unroll") for (int _i = 0; _i < 2; ++_i) \
;         __builtin_amdgcn_global_load_lds((const unsigned*)((const char*)(gbase) + (voff)[_i]), (PG8_LAS unsigned*)(lds + (bufoff) + ldsw + _i * 8192), 16, 0, AUX_A); } while (0)
; #define PG8_STAGEB(bufoff, gbase, voff) do { _Pragma("unroll") for (int _i = 0; _i < 2; ++_i) \
;         __builtin_amdgcn_global_load_lds((const unsigned*)((const char*)(gbase) + (voff)[_i]), (PG8_LAS unsigned*)(lds + (bufoff) + ldsw + _i * 8192), 16, 0, AUX_B); } while (0)
; #define PG8_WAIT_V(n) asm volatile("s_waitcnt vmcnt(" #n ")" ::: "memory")
; #define PG8_BAR __builtin_amdgcn_s_barrier()
;     __device__ __forceinline__ void operator()(const f32x4 (&acc)[2][2][4][2], const Unit& u, int wr, int wc, int fr, int fq) const {
;     ...
;             if (fr == 0 && fq == 0) __hip_atomic_fetch_add(flag, 1u, __ATOMIC_RELAXED, __HIP_MEMORY_SCOPE_AGENT);
; template <class Epi, class Sched, bool ALIGN_EPI = false, bool SP2 = false>
; __device__ __forceinline__ void gemm_phase(PG8_LAS unsigned char* lds, const Gemm g, const Sched& S, const Epi& E) {
;     ...
;         PG8_STAGEB(PG8_SB(1, 0), sB1, voffB); PG8_STAGE(PG8_SA(1, 0), sA1, voffA); PG8_STAGEB(PG8_SB(1, 1), sB1 + hstep, voffB);
;         PG8_WAIT_V(6); PG8_BAR;
.LBB0_1056:
	v_bfe_u32 v18, v16, 4, 2
	s_lshl_b32 s0, s0, 5
	v_and_b32_e32 v17, 15, v16
	v_lshlrev_b32_e32 v19, 4, v18
	v_lshlrev_b32_e32 v16, 2, v16
	s_and_b32 s2, s0, 0x60
	s_add_i32 m0, s71, 0x18000
	v_lshl_add_u64 v[8:9], v[8:9], 0, s[76:77]
	v_lshl_or_b32 v1, s1, 6, v17
	v_lshl_or_b32 v19, v17, 6, v19
	s_lshl_b32 s1, s1, 13
	v_and_b32_e32 v16, 32, v16
	s_lshl_b32 s0, s2, 7
	global_load_lds_dwordx4 v[8:9], off
	v_lshl_add_u64 v[6:7], v[6:7], 0, s[76:77]
	s_add_i32 m0, s71, 0x1a000
	s_add_i32 s83, s71, 0x8000
	s_add_i32 s88, s71, 0xa000
	v_bitop3_b32 v99, v19, s0, v16 bitop3:0xde
	global_load_lds_dwordx4 v[6:7], off
	v_lshl_add_u64 v[2:3], v[2:3], 0, s[76:77]
	s_mov_b32 m0, s83
	s_add_u32 s0, s42, 0x40080
	v_bitop3_b32 v20, v19, s1, v16 bitop3:0xde
	global_load_lds_dwordx4 v[2:3], off
	v_lshl_add_u64 v[2:3], v[4:5], 0, s[76:77]
	s_mov_b32 m0, s88
	s_addc_u32 s1, s43, 0
	global_load_lds_dwordx4 v[2:3], off
	s_add_i32 m0, s71, 0x1c000
	v_lshl_add_u64 v[2:3], s[0:1], 0, v[136:137]
	global_load_lds_dwordx4 v[2:3], off
	v_lshl_add_u64 v[2:3], s[0:1], 0, v[132:133]
	s_add_i32 m0, s71, 0x1e000
	v_lshl_or_b32 v150, v18, 3, s2
	global_load_lds_dwordx4 v[2:3], off
	v_or_b32_e32 v2, v18, v17
	v_cmp_eq_u32_e64 s[40:41], 0, v2
	v_lshlrev_b32_e32 v2, 14, v10
	v_and_b32_e32 v2, 0xffff8000, v2
	v_lshl_add_u32 v2, v11, 11, v2
	v_and_b32_e32 v3, 1, v10
	v_lshl_or_b32 v2, v3, 6, v2
	v_lshl_add_u32 v140, v12, 1, v2
	v_lshlrev_b32_e32 v2, 14, v14
	v_and_b32_e32 v2, 0xffff8000, v2
	v_readlane_b32 s2, v253, 1
	s_waitcnt vmcnt(6)
	v_lshl_add_u32 v2, v13, 11, v2
	v_and_b32_e32 v3, 1, v14
	v_readlane_b32 s3, v253, 2
	s_cmpk_lt_u32 s12, 0x100
	v_lshl_or_b32 v2, v3, 6, v2
	s_mov_b32 s91, s2
	v_readlane_b32 s2, v252, 61
	s_cselect_b64 s[12:13], -1, 0
	s_mov_b32 s0, 0
	v_mov_b32_e32 v141, v98
	v_lshl_add_u32 v142, v15, 1, v2
	v_mov_b32_e32 v143, v98
	v_add_u32_e32 v151, 0, v20
	s_mov_b32 s90, s2
	s_barrier
	v_readlane_b32 s3, v252, 62
	s_branch .LBB0_1059

; #define PG8_STAGE(bufoff, gbase, voff) do { _Pragma("unroll") for (int _i = 0; _i < 2; ++_i) \
;         __builtin_amdgcn_global_load_lds((const unsigned*)((const char*)(gbase) + (voff)[_i]), (PG8_LAS unsigned*)(lds + (bufoff) + ldsw + _i * 8192), 16, 0, AUX_A); } while (0)
; #define PG8_STAGEB(bufoff, gbase, voff) do { _Pragma("unroll") for (int _i = 0; _i < 2; ++_i) \
;         __builtin_amdgcn_global_load_lds((const unsigned*)((const char*)(gbase) + (voff)[_i]), (PG8_LAS unsigned*)(lds + (bufoff) + ldsw + _i * 8192), 16, 0, AUX_B); } while (0)
; #define PG8_WAIT_V(n) asm volatile("s_waitcnt vmcnt(" #n ")" ::: "memory")
; #define PG8_BAR __builtin_amdgcn_s_barrier()
; template <class Epi, class Sched, bool ALIGN_EPI = false, bool SP2 = false>
; __device__ __forceinline__ void gemm_phase(PG8_LAS unsigned char* lds, const Gemm g, const Sched& S, const Epi& E) {
;     ...
;     const int aoff = lds_byte(wr * 64 + fr, fq * 8), boff = lds_byte(wc * 32 + fr, fq * 8);
;     ...
;         PG8_STAGEB(PG8_SB(1, 0), sB1, voffB); PG8_STAGE(PG8_SA(1, 0), sA1, voffA); PG8_STAGEB(PG8_SB(1, 1), sB1 + hstep, voffB);
;         PG8_WAIT_V(6); PG8_BAR;
.LBB0_1146:
	s_add_u32 s14, s4, 0x2d180000
	v_lshrrev_b32_e32 v18, 1, v16
	s_addc_u32 s15, s5, 0
	v_and_b32_e32 v18, 24, v18
	s_lshl_b32 s0, s0, 5
	v_and_b32_e32 v17, 15, v16
	v_lshlrev_b32_e32 v19, 1, v18
	v_lshlrev_b32_e32 v16, 2, v16
	s_and_b32 s2, s0, 0x60
	s_add_i32 m0, s71, 0x18000
	v_lshl_add_u64 v[8:9], v[8:9], 0, s[76:77]
	v_lshl_or_b32 v1, s1, 6, v17
	v_lshl_or_b32 v17, v17, 6, v19
	s_lshl_b32 s1, s1, 13
	v_and_b32_e32 v16, 32, v16
	s_lshl_b32 s0, s2, 7
	global_load_lds_dwordx4 v[8:9], off
	v_lshl_add_u64 v[6:7], v[6:7], 0, s[76:77]
	s_add_i32 m0, s71, 0x1a000
	s_add_i32 s83, s71, 0x8000
	s_add_i32 s88, s71, 0xa000
	v_bitop3_b32 v99, v17, s0, v16 bitop3:0xde
	global_load_lds_dwordx4 v[6:7], off
	v_lshl_add_u64 v[2:3], v[2:3], 0, s[76:77]
	s_mov_b32 m0, s83
	s_add_u32 s0, s50, 0x40080
	v_bitop3_b32 v19, v17, s1, v16 bitop3:0xde
	global_load_lds_dwordx4 v[2:3], off
	v_lshl_add_u64 v[2:3], v[4:5], 0, s[76:77]
	s_mov_b32 m0, s88
	s_addc_u32 s1, s51, 0
	global_load_lds_dwordx4 v[2:3], off
	s_add_i32 m0, s71, 0x1c000
	v_lshl_add_u64 v[2:3], s[0:1], 0, v[136:137]
	global_load_lds_dwordx4 v[2:3], off
	v_lshl_add_u64 v[2:3], s[0:1], 0, v[132:133]
	s_add_i32 m0, s71, 0x1e000
	v_or_b32_e32 v152, s2, v18
	global_load_lds_dwordx4 v[2:3], off
	v_lshlrev_b32_e32 v2, 14, v10
	v_and_b32_e32 v2, 0xffff8000, v2
	v_lshl_add_u32 v2, v11, 11, v2
	v_and_b32_e32 v3, 1, v10
	v_lshl_or_b32 v2, v3, 6, v2
	v_lshl_add_u32 v140, v12, 1, v2
	v_lshlrev_b32_e32 v2, 14, v14
	v_and_b32_e32 v2, 0xffff8000, v2
	v_readlane_b32 s2, v253, 1
	s_waitcnt vmcnt(6)
	v_lshl_add_u32 v2, v13, 11, v2
	v_and_b32_e32 v3, 1, v14
	v_readlane_b32 s3, v253, 2
	s_cmpk_lt_u32 s16, 0x100
	v_lshl_or_b32 v2, v3, 6, v2
	s_mov_b32 s91, s2
	v_readlane_b32 s2, v252, 61
	s_cselect_b64 s[16:17], -1, 0
	v_mov_b32_e32 v141, v98
	v_lshl_add_u32 v142, v15, 1, v2
	v_mov_b32_e32 v143, v98
	s_mov_b32 s0, 0
	v_add_u32_e32 v153, 0, v19
	s_mov_b32 s90, s2
	s_barrier
	v_readlane_b32 s3, v252, 62
	s_branch .LBB0_1149

; #define PG8_STAGE(bufoff, gbase, voff) do { _Pragma("unroll") for (int _i = 0; _i < 2; ++_i) \
;         __builtin_amdgcn_global_load_lds((const unsigned*)((const char*)(gbase) + (voff)[_i]), (PG8_LAS unsigned*)(lds + (bufoff) + ldsw + _i * 8192), 16, 0, AUX_A); } while (0)
; #define PG8_STAGEB(bufoff, gbase, voff) do { _Pragma("unroll") for (int _i = 0; _i < 2; ++_i) \
;         __builtin_amdgcn_global_load_lds((const unsigned*)((const char*)(gbase) + (voff)[_i]), (PG8_LAS unsigned*)(lds + (bufoff) + ldsw + _i * 8192), 16, 0, AUX_B); } while (0)
; #define PG8_WAIT_V(n) asm volatile("s_waitcnt vmcnt(" #n ")" ::: "memory")
; #define PG8_BAR __builtin_amdgcn_s_barrier()
;     __device__ __forceinline__ void operator()(const f32x4 (&acc)[2][2][4][2], const Unit& u, int wr, int wc, int fr, int fq) const {
;         const int col0 = u.pn * BM + wc * 32 + 8 * fq;
;         const bool part = u.slab >= 0;
; #pragma unroll
;         for (int ai = 0; ai < 2; ++ai) {
;             const int rb = u.pm * BM + ai * HALF + wr * 64;
;             const int cb = rb < 8192 ? (rb >> 11) : 4 + ((rb - 8192) >> 6);
;             const float* g = gmod + (size_t)cb * 12288 + col0;
; template <class Epi, class Sched, bool ALIGN_EPI = false, bool SP2 = false>
; __device__ __forceinline__ void gemm_phase(PG8_LAS unsigned char* lds, const Gemm g, const Sched& S, const Epi& E) {
;     ...
;         PG8_STAGEB(PG8_SB(1, 0), sB1, voffB); PG8_STAGE(PG8_SA(1, 0), sA1, voffA); PG8_STAGEB(PG8_SB(1, 1), sB1 + hstep, voffB);
;         PG8_WAIT_V(6); PG8_BAR;
.LBB0_1294:
	s_add_u32 s6, s8, 0x39880000
	s_mul_i32 s11, s64, 0xf0000
	s_addc_u32 s7, s9, 0
	s_mul_hi_u32 s2, s64, 0xf0000
	s_add_u32 s11, s8, s11
	s_addc_u32 s2, s9, s2
	s_add_u32 s54, s11, 0x104000
	s_addc_u32 s55, s2, 0
	s_add_u32 s56, s8, 0x35880000
	v_lshrrev_b32_e32 v17, 1, v16
	s_addc_u32 s57, s9, 0
	v_and_b32_e32 v17, 24, v17
	s_lshl_b32 s0, s0, 5
	v_and_b32_e32 v1, 15, v16
	v_lshlrev_b32_e32 v18, 1, v17
	v_lshlrev_b32_e32 v16, 2, v16
	s_and_b32 s2, s0, 0x60
	s_add_i32 m0, s50, 0x18000
	v_lshl_add_u64 v[8:9], v[8:9], 0, s[76:77]
	s_lshl_b32 s58, s1, 6
	v_lshl_or_b32 v18, v1, 6, v18
	s_lshl_b32 s1, s1, 13
	v_and_b32_e32 v16, 32, v16
	s_lshl_b32 s0, s2, 7
	global_load_lds_dwordx4 v[8:9], off
	v_lshl_add_u64 v[6:7], v[6:7], 0, s[76:77]
	s_add_i32 m0, s50, 0x1a000
	s_add_i32 s59, s50, 0x8000
	s_add_i32 s60, s50, 0xa000
	v_bitop3_b32 v99, v18, s0, v16 bitop3:0xde
	global_load_lds_dwordx4 v[6:7], off
	v_lshl_add_u64 v[2:3], v[2:3], 0, s[76:77]
	s_mov_b32 m0, s59
	s_add_u32 s0, s34, 0x80080
	v_bitop3_b32 v19, v18, s1, v16 bitop3:0xde
	global_load_lds_dwordx4 v[2:3], off
	v_lshl_add_u64 v[2:3], v[4:5], 0, s[76:77]
	s_mov_b32 m0, s60
	s_addc_u32 s1, s35, 0
	global_load_lds_dwordx4 v[2:3], off
	s_add_i32 m0, s50, 0x1c000
	v_lshl_add_u64 v[2:3], s[0:1], 0, v[156:157]
	global_load_lds_dwordx4 v[2:3], off
	v_lshl_add_u64 v[2:3], s[0:1], 0, v[152:153]
	s_add_i32 m0, s50, 0x1e000
	s_cmpk_lt_u32 s10, 0x100
	global_load_lds_dwordx4 v[2:3], off
	v_lshlrev_b32_e32 v2, 15, v10
	v_and_b32_e32 v2, 0xffff0000, v2
	v_lshl_add_u32 v2, v11, 12, v2
	v_and_b32_e32 v3, 1, v10
	v_lshl_or_b32 v2, v3, 6, v2
	v_lshl_add_u32 v160, v12, 1, v2
	v_lshlrev_b32_e32 v2, 15, v14
	v_and_b32_e32 v2, 0xffff0000, v2
	s_waitcnt vmcnt(6)
	v_lshl_add_u32 v2, v13, 12, v2
	v_and_b32_e32 v3, 1, v14
	v_lshl_or_b32 v2, v3, 6, v2
	v_readlane_b32 s0, v252, 45
	s_cselect_b64 s[8:9], -1, 0
	v_or_b32_e32 v180, s2, v17
	v_mov_b32_e32 v161, v98
	v_lshl_add_u32 v162, v15, 1, v2
	v_mov_b32_e32 v163, v98
	s_mov_b32 s61, 0
	v_add_u32_e32 v181, 0, v19
	s_mov_b32 s78, s0
	v_readlane_b32 s71, v252, 46
	v_readlane_b32 s70, v252, 59
	v_readlane_b32 s69, v252, 57
	s_mov_b32 s3, 0x20000
	s_mov_b32 s46, 0x30000
	s_barrier
	s_branch .LBB0_1297

; #define PG8_STAGE(bufoff, gbase, voff) do { _Pragma("unroll") for (int _i = 0; _i < 2; ++_i) \
;         __builtin_amdgcn_global_load_lds((const unsigned*)((const char*)(gbase) + (voff)[_i]), (PG8_LAS unsigned*)(lds + (bufoff) + ldsw + _i * 8192), 16, 0, AUX_A); } while (0)
; #define PG8_STAGEB(bufoff, gbase, voff) do { _Pragma("unroll") for (int _i = 0; _i < 2; ++_i) \
;         __builtin_amdgcn_global_load_lds((const unsigned*)((const char*)(gbase) + (voff)[_i]), (PG8_LAS unsigned*)(lds + (bufoff) + ldsw + _i * 8192), 16, 0, AUX_B); } while (0)
; #define PG8_WAIT_V(n) asm volatile("s_waitcnt vmcnt(" #n ")" ::: "memory")
; #define PG8_BAR __builtin_amdgcn_s_barrier()
; template <class Epi, class Sched, bool ALIGN_EPI = false, bool SP2 = false>
; __device__ __forceinline__ void gemm_phase(PG8_LAS unsigned char* lds, const Gemm g, const Sched& S, const Epi& E) {
;     ...
;     const int aoff = lds_byte(wr * 64 + fr, fq * 8), boff = lds_byte(wc * 32 + fr, fq * 8);
;     ...
;         PG8_STAGEB(PG8_SB(1, 0), sB1, voffB); PG8_STAGE(PG8_SA(1, 0), sA1, voffA); PG8_STAGEB(PG8_SB(1, 1), sB1 + hstep, voffB);
;         PG8_WAIT_V(6); PG8_BAR;
.LBB0_1452:
	s_add_u32 s8, s4, 0x2f580000
	v_lshrrev_b32_e32 v18, 1, v16
	s_addc_u32 s9, s5, 0
	v_and_b32_e32 v18, 24, v18
	s_lshl_b32 s0, s0, 5
	v_and_b32_e32 v17, 15, v16
	v_lshlrev_b32_e32 v19, 1, v18
	v_lshlrev_b32_e32 v16, 2, v16
	s_and_b32 s2, s0, 0x60
	s_add_i32 m0, s57, 0x18000
	v_lshl_add_u64 v[8:9], v[8:9], 0, s[76:77]
	v_lshl_or_b32 v1, s1, 6, v17
	v_lshl_or_b32 v17, v17, 6, v19
	s_lshl_b32 s1, s1, 13
	v_and_b32_e32 v16, 32, v16
	s_lshl_b32 s0, s2, 7
	global_load_lds_dwordx4 v[8:9], off
	v_lshl_add_u64 v[6:7], v[6:7], 0, s[76:77]
	s_add_i32 m0, s57, 0x1a000
	s_add_i32 s61, s57, 0x8000
	s_add_i32 s62, s57, 0xa000
	v_bitop3_b32 v99, v17, s0, v16 bitop3:0xde
	global_load_lds_dwordx4 v[6:7], off
	s_add_u32 s0, s34, 0x80080
	v_bitop3_b32 v19, v17, s1, v16 bitop3:0xde
	s_addc_u32 s1, s35, 0
	s_add_i32 m0, s57, 0x1c000
	v_lshl_add_u64 v[2:3], s[0:1], 0, v[136:137]
	global_load_lds_dwordx4 v[2:3], off
	v_lshl_add_u64 v[2:3], s[0:1], 0, v[132:133]
	s_add_i32 m0, s57, 0x1e000
	s_cmpk_lt_u32 s10, 0x100
	global_load_lds_dwordx4 v[2:3], off
	v_lshlrev_b32_e32 v2, 15, v10
	v_and_b32_e32 v2, 0xffff0000, v2
	v_lshl_add_u32 v2, v11, 12, v2
	v_and_b32_e32 v3, 1, v10
	v_lshl_or_b32 v2, v3, 6, v2
	v_lshl_add_u32 v140, v12, 1, v2
	v_lshlrev_b32_e32 v2, 15, v14
	v_and_b32_e32 v2, 0xffff0000, v2
	s_waitcnt vmcnt(4)
	v_lshl_add_u32 v2, v13, 12, v2
	v_and_b32_e32 v3, 1, v14
	v_lshl_or_b32 v2, v3, 6, v2
	v_readlane_b32 s0, v252, 37
	s_cselect_b64 s[10:11], -1, 0
	v_or_b32_e32 v148, s2, v18
	v_mov_b32_e32 v141, v98
	v_lshl_add_u32 v142, v15, 1, v2
	v_mov_b32_e32 v143, v98
	s_mov_b32 s63, 0
	v_add_u32_e32 v149, 0, v19
	v_readlane_b32 s69, v253, 6
	s_mov_b32 s70, s0
	s_movk_i32 s3, 0xc7
	s_mov_b32 s64, 0x58000
	s_mov_b32 s65, 0x2c000
	s_mov_b32 s66, 0x84000
	s_barrier
	v_readlane_b32 s1, v252, 38
	s_branch .LBB0_1455

; #define PG8_STAGE(bufoff, gbase, voff) do { _Pragma("unroll") for (int _i = 0; _i < 2; ++_i) \
;         __builtin_amdgcn_global_load_lds((const unsigned*)((const char*)(gbase) + (voff)[_i]), (PG8_LAS unsigned*)(lds + (bufoff) + ldsw + _i * 8192), 16, 0, AUX_A); } while (0)
; #define PG8_STAGEB(bufoff, gbase, voff) do { _Pragma("unroll") for (int _i = 0; _i < 2; ++_i) \
;         __builtin_amdgcn_global_load_lds((const unsigned*)((const char*)(gbase) + (voff)[_i]), (PG8_LAS unsigned*)(lds + (bufoff) + ldsw + _i * 8192), 16, 0, AUX_B); } while (0)
; #define PG8_WAIT_V(n) asm volatile("s_waitcnt vmcnt(" #n ")" ::: "memory")
; #define PG8_BAR __builtin_amdgcn_s_barrier()
; template <class Epi, class Sched, bool ALIGN_EPI = false, bool SP2 = false>
; __device__ __forceinline__ void gemm_phase(PG8_LAS unsigned char* lds, const Gemm g, const Sched& S, const Epi& E) {
;     ...
;     for (int i = 0; i < 2; ++i) { int R, C; stage_rc(tid * 16 + i * 8192, R, C); const int Rb = Epi::PERM ? ((R & ~31) + perm32(R & 31)) : R;
;         voffA[i] = (unsigned)(R * K + C) * 2u; voffB[i] = (unsigned)(Rb * K + C) * 2u; }
;     ...
;         PG8_STAGEB(PG8_SB(1, 0), sB1, voffB); PG8_STAGE(PG8_SA(1, 0), sA1, voffA); PG8_STAGEB(PG8_SB(1, 1), sB1 + hstep, voffB);
;         PG8_WAIT_V(6); PG8_BAR;
.LBB0_1641:
	s_cmp_eq_u32 s8, 3
	s_cselect_b32 s7, s65, 0
	s_cselect_b32 s6, s64, 0
	s_cmp_lg_u64 s[6:7], 0
	s_cselect_b64 s[8:9], -1, 0
	s_add_u32 s10, s12, 0x39880000
	s_addc_u32 s11, s13, 0
	v_readlane_b32 s2, v254, 57
	s_add_u32 s2, s12, s2
	v_readlane_b32 s3, v254, 56
	s_addc_u32 s15, s13, s3
	s_add_u32 s55, s2, 0x10a000
	s_addc_u32 s56, s15, 0
	s_add_u32 s57, s12, 0x35880000
	v_lshrrev_b32_e32 v19, 1, v18
	s_addc_u32 s58, s13, 0
	v_and_b32_e32 v19, 24, v19
	s_lshl_b32 s0, s0, 5
	v_and_b32_e32 v1, 15, v18
	v_lshlrev_b32_e32 v20, 1, v19
	v_lshlrev_b32_e32 v18, 2, v18
	s_and_b32 s2, s0, 0x60
	s_add_i32 m0, s50, 0x18000
	v_lshl_add_u64 v[8:9], v[8:9], 0, s[76:77]
	s_lshl_b32 s59, s1, 6
	v_lshl_or_b32 v20, v1, 6, v20
	s_lshl_b32 s1, s1, 13
	v_and_b32_e32 v18, 32, v18
	s_lshl_b32 s0, s2, 7
	global_load_lds_dwordx4 v[8:9], off
	v_lshl_add_u64 v[6:7], v[6:7], 0, s[76:77]
	s_add_i32 m0, s50, 0x1a000
	s_add_i32 s60, s50, 0x8000
	s_add_i32 s61, s50, 0xa000
	v_bitop3_b32 v99, v20, s0, v18 bitop3:0xde
	global_load_lds_dwordx4 v[6:7], off
	v_lshl_add_u64 v[2:3], v[2:3], 0, s[76:77]
	s_mov_b32 m0, s60
	s_add_u32 s0, s34, 0x160080
	v_bitop3_b32 v21, v20, s1, v18 bitop3:0xde
	global_load_lds_dwordx4 v[2:3], off
	v_lshl_add_u64 v[2:3], v[4:5], 0, s[76:77]
	s_mov_b32 m0, s61
	s_addc_u32 s1, s35, 0
	global_load_lds_dwordx4 v[2:3], off
	s_add_i32 m0, s50, 0x1c000
	v_lshl_add_u64 v[2:3], s[0:1], 0, v[160:161]
	global_load_lds_dwordx4 v[2:3], off
	v_lshl_add_u64 v[2:3], s[0:1], 0, v[156:157]
	s_add_i32 m0, s50, 0x1e000
	v_or_b32_e32 v188, s2, v19
	global_load_lds_dwordx4 v[2:3], off
	s_movk_i32 s2, 0x1600
	v_lshrrev_b32_e32 v3, 1, v10
	v_mul_lo_u32 v2, v11, s2
	s_mov_b32 s3, 0x16000
	v_mad_u64_u32 v[2:3], s[0:1], v3, s3, v[2:3]
	v_or_b32_e32 v2, v2, v12
	v_add_lshl_u32 v164, v2, v13, 1
	v_lshrrev_b32_e32 v3, 1, v15
	v_mul_lo_u32 v2, v14, s2
	s_waitcnt vmcnt(6)
	v_mad_u64_u32 v[2:3], s[0:1], v3, s3, v[2:3]
	s_cmpk_lt_u32 s14, 0x100
	v_or_b32_e32 v2, v2, v16
	v_readlane_b32 s0, v252, 45
	s_mov_b32 s54, 0
	s_cselect_b64 s[12:13], -1, 0
	v_mov_b32_e32 v165, v98
	v_add_lshl_u32 v166, v2, v17, 1
	v_mov_b32_e32 v167, v98
	v_add_u32_e32 v189, 0, v21
	s_mov_b32 s78, s0
	v_readlane_b32 s82, v252, 42
	v_readlane_b32 s75, v252, 59
	v_readlane_b32 s71, v252, 57
	s_mov_b32 s3, 0x20000
	s_mov_b32 s47, 0x30000
	s_mov_b64 s[64:65], 0x40000
	s_mov_b64 s[66:67], 0x10000
	s_barrier
	s_branch .LBB0_1644
